# MLA phase rewritten by hand on v_mfma_f32_16x16x32_bf16: S^T 16x16 blocks, P^T used as B operand straight from accumulators (no permlane), conflict-free K/V LDS images; plus SWA staging
# speedup vs baseline: 1.0535x; 1.0485x over previous
; template <bool MLA> __device__ __forceinline__ void attn_unit(const AttnP& P, int b, int hh, int qb, LAS char* lds) {
;     constexpr int DV = MLA ? 128 : 64, NCB = DV / 32, NQF = MLA ? 12 : 4;
;     constexpr int KBYTES = MLA ? 24576 : 8192, VBYTES = 64 * DV * 2;
;     constexpr int SC9 = MLA ? 72168784 : 125000000;
;     constexpr float SCALE = SC9 * 1e-9f;
;     constexpr int W = MLA ? (1 << 30) : 128;
;     const int tid = threadIdx.x, wid = __builtin_amdgcn_readfirstlane(tid >> 6), lane = tid & 63, r32 = lane & 31, hi = lane >> 5;
;     LAS char* V_lds = lds; LAS char* K_lds = lds + 2 * VBYTES;
;     LAS float* ws = (LAS float*)(lds + 2 * VBYTES + 2 * KBYTES) + wid * 64; LAS float* li_l = ws; LAS float* al_l = ws + 32;
;     LAS float* bias_l = (LAS float*)(lds + 2 * VBYTES + 2 * KBYTES + 2048);
;     const int q0 = qb * 256; const size_t rowbase = (size_t)b * SEQ;
;     const int jt0 = MLA ? 0 : (q0 == 0 ? 0 : -2);
;     const int NT = MLA ? 4 * qb + 4 : 4 - jt0;
;     const int kbase0 = MLA ? 0 : q0 + 64 * jt0;
;     const int qlo = q0 + wid * 32, qm = qlo + r32 - 4 * hi;
;     bf16x8 qr[NQF];
;     const size_t qrow = rowbase + qlo + r32;
;     if constexpr (MLA) {
; #pragma unroll
;         for (int d0 = 0; d0 < 8; ++d0) qr[d0] = *(const bf16x8*)(P.QN + qrow * 2048 + hh * 128 + d0 * 16 + hi * 8);
; #pragma unroll
;         for (int d0 = 0; d0 < 4; ++d0) qr[8 + d0] = *(const bf16x8*)(P.QR + qrow * 1024 + hh * 64 + d0 * 16 + hi * 8);
;     } else {
; #pragma unroll
;         for (int d0 = 0; d0 < 4; ++d0) qr[d0] = *(const bf16x8*)(P.QS + qrow * 2048 + hh * 64 + d0 * 16 + hi * 8);
;         if (tid < 128) bias_l[tid] = P.rel[(int)T5B[tid] * 32 + hh] * (1.0f / SCALE);
;     }
;     bf16x8 sk0, sv0;
;     const int sr8 = tid >> 3, ch8 = tid & 7;
;     const bf16_t* Kg; const bf16_t* Vg; const bf16_t* Rg = nullptr;
;     unsigned okA = 0, okB = 0, orp = 0, ovA = 0, ovB = 0;
;     if constexpr (MLA) {
;         Kg = P.KN + rowbase * 2048 + hh * 128; Vg = P.V + rowbase * 2048 + hh * 128; Rg = P.KR + rowbase * 64;
;         { const int rA = 4 * wid + (lane >> 4), rB = rA + 32, cp = lane & 15; okA = (unsigned)(rA * 2048 + ((cp ^ (rA & 7)) << 3)); okB = (unsigned)(rB * 2048 + ((cp ^ (rB & 7)) << 3)); }
;         { const int rr = 8 * wid + (lane >> 3), cp = lane & 7; orp = (unsigned)(rr * 64 + ((cp ^ (rr & 7)) << 3)); }
.LBB0_301:
	s_cmp_lt_i32 s54, 4
	s_cselect_b64 s[4:5], -1, 0
	s_and_b64 s[44:45], s[4:5], s[0:1]
	s_andn2_b64 vcc, exec, s[44:45]
	s_cbranch_vccnz .LBB0_682
	s_cmpk_gt_i32 s2, 0x3ff
	v_lshrrev_b32_e32 v1, 5, v206
	v_and_b32_e32 v198, 7, v162
	v_lshrrev_b32_e32 v200, 2, v162
	v_lshlrev_b32_e32 v147, 3, v162
	v_lshlrev_b32_e32 v199, 1, v162
	v_cmp_gt_u32_e64 s[0:1], 32, v206
	v_and_b32_e32 v151, 1, v162
	s_cbranch_scc1 .LBB0_597
	v_readfirstlane_b32 s4, v162
	s_nop 3
	s_lshr_b32 s4, s4, 6
	s_lshl_b32 s5, s4, 10
	s_add_u32 s6, s52, 0x1e000000
	s_addc_u32 s7, s53, 0
	s_add_u32 s8, s52, 0x26000000
	s_addc_u32 s9, s53, 0
	s_add_u32 s12, s52, 0x2a000000
	s_addc_u32 s13, s53, 0
	s_add_u32 s14, s52, 0x13c00000
	s_addc_u32 s15, s53, 0
	s_add_u32 s16, s52, 0x32000000
	s_addc_u32 s17, s53, 0
	s_mov_b32 s72, 0x4138aa3b
	v_mov_b32_e32 v245, 0xff800000
	v_mov_b32_e32 v248, 0
	v_and_b32_e32 v221, 15, v206
	v_lshrrev_b32_e32 v222, 4, v206
	v_lshrrev_b32_e32 v223, 1, v221
	v_xor_b32_e32 v223, v223, v222
	v_lshlrev_b32_e32 v223, 4, v223
	v_lshl_or_b32 v224, v221, 7, v223
	v_xor_b32_e32 v225, 64, v224
	v_lshrrev_b32_e32 v223, 1, v222
	v_lshlrev_b32_e32 v223, 11, v223
	v_and_b32_e32 v220, 1, v222
	v_lshl_or_b32 v223, v220, 8, v223
	v_lshrrev_b32_e32 v226, 2, v221
	v_lshl_or_b32 v223, v226, 6, v223
	v_and_b32_e32 v226, 3, v221
	v_lshl_or_b32 v223, v226, 3, v223
	v_lshlrev_b32_e32 v220, 5, v220
	v_or_b32_e32 v226, v223, v220
	v_xor_b32_e32 v220, 32, v220
	v_or_b32_e32 v227, v223, v220
	v_lshlrev_b32_e32 v223, 2, v222
	v_sub_u32_e32 v243, v221, v223
	v_xor_b32_e32 v246, 16, v206
	v_lshlrev_b32_e32 v246, 2, v246
	v_xor_b32_e32 v247, 32, v206
	v_lshlrev_b32_e32 v247, 2, v247
	v_lshlrev_b32_e32 v223, 4, v222
	v_lshl_or_b32 v237, v221, 12, v223
	v_add_u32_e32 v238, 0x10000, v237
	v_lshl_or_b32 v239, v221, 11, v223
	v_add_u32_e32 v240, 0x8000, v239
	v_lshlrev_b32_e32 v223, 3, v222
	v_lshl_or_b32 v241, v221, 12, v223
	v_add_u32_e32 v242, 0x10000, v241
	v_bfe_u32 v221, v162, 4, 3
	v_bitop3_b32 v221, v221, v162, 7 bitop3:0x78
	v_lshlrev_b32_e32 v221, 4, v221
	v_lshrrev_b32_e32 v222, 3, v162
	v_lshl_or_b32 v232, v222, 12, v221
	v_add_u32_e32 v233, 0x80, v232
	v_lshl_or_b32 v234, v222, 7, v221
	v_bfe_u32 v221, v206, 2, 3
	v_lshrrev_b32_e32 v222, 2, v221
	v_lshlrev_b32_e32 v222, 1, v222
	v_and_b32_e32 v223, 3, v206
	v_xor_b32_e32 v223, v223, v222
	v_lshlrev_b32_e32 v223, 4, v223
	v_lshrrev_b32_e32 v222, 5, v206
	v_lshl_or_b32 v223, v222, 6, v223
	s_lshr_b32 s36, s4, 1
	s_lshl_b32 s36, s36, 15
	s_and_b32 s37, s4, 1
	s_lshl_b32 s37, s37, 7
	s_add_i32 s36, s36, s37
	v_lshl_or_b32 v223, v221, 12, v223
	v_add_u32_e32 v235, s36, v223
	v_add_u32_e32 v236, 0x20000, v235
	s_mov_b32 s28, s2
.Lm16_item:
	s_mov_b32 s29, 0
.Lm16_unit:
	s_and_b32 s33, s28, 31
	s_cmp_eq_u32 s29, 0
	s_cbranch_scc0 .Lm16_qb_ok
	s_sub_u32 s33, 63, s33
.Lm16_qb_ok:
	s_lshr_b32 s36, s28, 5
	s_and_b32 s63, s36, 15
	s_lshr_b32 s64, s36, 4
	s_lshl_b32 s40, s33, 2
	s_add_u32 s40, s40, 4
	s_lshl_b32 s43, s33, 8
	s_lshl_b32 s36, s4, 5
	s_add_u32 s43, s43, s36
	s_lshl_b32 s36, s64, 14
	s_add_u32 s36, s36, s43
	s_lshl_b32 s37, s36, 12
	s_lshl_b32 s59, s63, 8
	s_add_u32 s37, s37, s59
	s_add_u32 s66, s6, s37
	s_addc_u32 s67, s7, 0
	s_lshl_b32 s37, s36, 11
	s_lshl_b32 s59, s63, 7
	s_add_u32 s37, s37, s59
	s_add_u32 s68, s8, s37
	s_addc_u32 s69, s9, 0
	s_lshl_b32 s37, s64, 26
	s_lshl_b32 s59, s63, 8
	s_add_u32 s37, s37, s59
	s_add_u32 s46, s12, s37
	s_addc_u32 s47, s13, 0
	s_add_u32 s48, s16, s37
	s_addc_u32 s49, s17, 0
	s_lshl_b32 s37, s64, 21
	s_add_u32 s50, s14, s37
	s_addc_u32 s51, s15, 0
	global_load_dwordx4 v[66:69], v237, s[66:67] offset:0
	global_load_dwordx4 v[70:73], v237, s[66:67] offset:64
	global_load_dwordx4 v[74:77], v237, s[66:67] offset:128
	global_load_dwordx4 v[78:81], v237, s[66:67] offset:192
	global_load_dwordx4 v[82:85], v239, s[68:69] offset:0
	global_load_dwordx4 v[86:89], v239, s[68:69] offset:64
	global_load_dwordx4 v[90:93], v238, s[66:67] offset:0
	global_load_dwordx4 v[94:97], v238, s[66:67] offset:64
	global_load_dwordx4 v[98:101], v238, s[66:67] offset:128
	global_load_dwordx4 v[102:105], v238, s[66:67] offset:192
	global_load_dwordx4 v[106:109], v240, s[68:69] offset:0
	global_load_dwordx4 v[110:113], v240, s[68:69] offset:64
	s_mov_b32 s70, 0x8000
	s_mov_b32 s71, 0
	s_add_i32 s36, s5, s70
	s_mov_b32 m0, s36
	s_nop 0
	global_load_lds_dwordx4 v232, s[46:47]
	s_add_i32 m0, s36, 0x2000
	s_nop 0
	global_load_lds_dwordx4 v233, s[46:47]
	s_add_i32 m0, s36, 0x4000
	s_nop 0
	global_load_lds_dwordx4 v234, s[50:51]
	s_add_i32 s36, s5, s71
	s_mov_b32 m0, s36
	s_nop 0
	global_load_lds_dwordx4 v235, s[48:49]
	s_add_i32 m0, s36, 0x2000
	s_nop 0
	global_load_lds_dwordx4 v236, s[48:49]
	s_add_u32 s46, s46, 0x40000
	s_addc_u32 s47, s47, 0
	s_add_u32 s48, s48, 0x40000
	s_addc_u32 s49, s49, 0
	s_add_u32 s50, s50, 0x2000
	s_addc_u32 s51, s51, 0
	v_mov_b32_e32 v2, 0
	v_mov_b32_e32 v3, 0
	v_mov_b32_e32 v4, 0
	v_mov_b32_e32 v5, 0
	v_mov_b32_e32 v6, 0
	v_mov_b32_e32 v7, 0
	v_mov_b32_e32 v8, 0
	v_mov_b32_e32 v9, 0
	v_mov_b32_e32 v10, 0
	v_mov_b32_e32 v11, 0
	v_mov_b32_e32 v12, 0
	v_mov_b32_e32 v13, 0
	v_mov_b32_e32 v14, 0
	v_mov_b32_e32 v15, 0
	v_mov_b32_e32 v16, 0
	v_mov_b32_e32 v17, 0
	v_mov_b32_e32 v18, 0
	v_mov_b32_e32 v19, 0
	v_mov_b32_e32 v20, 0
	v_mov_b32_e32 v21, 0
	v_mov_b32_e32 v22, 0
	v_mov_b32_e32 v23, 0
	v_mov_b32_e32 v24, 0
	v_mov_b32_e32 v25, 0
	v_mov_b32_e32 v26, 0
	v_mov_b32_e32 v27, 0
	v_mov_b32_e32 v28, 0
	v_mov_b32_e32 v29, 0
	v_mov_b32_e32 v30, 0
	v_mov_b32_e32 v31, 0
	v_mov_b32_e32 v32, 0
	v_mov_b32_e32 v33, 0
	v_mov_b32_e32 v34, 0
	v_mov_b32_e32 v35, 0
	v_mov_b32_e32 v36, 0
	v_mov_b32_e32 v37, 0
	v_mov_b32_e32 v38, 0
	v_mov_b32_e32 v39, 0
	v_mov_b32_e32 v40, 0
	v_mov_b32_e32 v41, 0
	v_mov_b32_e32 v42, 0
	v_mov_b32_e32 v43, 0
	v_mov_b32_e32 v44, 0
	v_mov_b32_e32 v45, 0
	v_mov_b32_e32 v46, 0
	v_mov_b32_e32 v47, 0
	v_mov_b32_e32 v48, 0
	v_mov_b32_e32 v49, 0
	v_mov_b32_e32 v50, 0
	v_mov_b32_e32 v51, 0
	v_mov_b32_e32 v52, 0
	v_mov_b32_e32 v53, 0
	v_mov_b32_e32 v54, 0
	v_mov_b32_e32 v55, 0
	v_mov_b32_e32 v56, 0
	v_mov_b32_e32 v57, 0
	v_mov_b32_e32 v58, 0
	v_mov_b32_e32 v59, 0
	v_mov_b32_e32 v60, 0
	v_mov_b32_e32 v61, 0
	v_mov_b32_e32 v62, 0
	v_mov_b32_e32 v63, 0
	v_mov_b32_e32 v64, 0
	v_mov_b32_e32 v65, 0
	v_mov_b32_e32 v216, 0
	v_mov_b32_e32 v218, 0
	v_mov_b32_e32 v208, 0
	v_mov_b32_e32 v209, 0
	v_mov_b32_e32 v210, 0
	v_mov_b32_e32 v211, 0
	v_mov_b32_e32 v217, 0
	v_mov_b32_e32 v219, 0
	v_mov_b32_e32 v212, 0
	v_mov_b32_e32 v213, 0
	v_mov_b32_e32 v214, 0
	v_mov_b32_e32 v215, 0
	s_mov_b32 s41, 0
	s_mov_b32 s42, 0
	s_waitcnt vmcnt(0)
	s_barrier
; #define WLK(n) do { asm volatile("s_waitcnt lgkmcnt(" #n ")" ::: "memory"); SBAR(); } while (0)
; #define RDN(S, dd, off) do { const int a_ = rb + (((dd) * 32 + h16) ^ sw); KRD(S##0, a_, off); KRD(S##1, a_, 8192 + (off)); } while (0)
; #define RDR(S, ks) do { const int a_ = rr + (((((ks) * 2 + hi)) ^ (r32 & 7)) << 4); KRD(S##0, a_, 0); KRD(S##1, a_, 4096); } while (0)
; #define MM1(S, d) do { p0 = __builtin_amdgcn_mfma_f32_32x32x16_bf16(S##0, qr[d], p0, 0, 0, 0); p1 = __builtin_amdgcn_mfma_f32_32x32x16_bf16(S##1, qr[d], p1, 0, 0, 0); } while (0)
; __device__ __forceinline__ void qk_mla(f32x16& p0, f32x16& p1, int kaddr, int r32, int hi, const bf16x8* qr) {
;     const int rb = kaddr + r32 * 256, sw = (r32 & 7) << 4, h16 = hi * 16;
;     const int rr = kaddr + 16384 + r32 * 128;
;     ...
;     bf16x8 A0, A1, B0, B1;
;     RDN(A, 0, 0); RDN(B, 1, 0);
;     WLK(2); MM1(A, 0); RDN(A, 2, 0);
;     WLK(2); MM1(B, 1); RDN(B, 3, 0);
;     WLK(2); MM1(A, 2); RDN(A, 0, 128);
;     WLK(2); MM1(B, 3); RDN(B, 1, 128);
;     WLK(2); MM1(A, 4); RDN(A, 2, 128);
;     WLK(2); MM1(B, 5); RDN(B, 3, 128);
;     WLK(2); MM1(A, 6); RDR(A, 0);
;     WLK(2); MM1(B, 7); RDR(B, 1);
;     WLK(2); MM1(A, 8); RDR(A, 2);
;     WLK(2); MM1(B, 9); RDR(B, 3);
;     WLK(2); MM1(A, 10);
;     WLK(0); MM1(B, 11);
; template <bool MLA> __device__ __forceinline__ void attn_unit(const AttnP& P, int b, int hh, int qb, LAS char* lds) {
;     ...
;     for (int t = 0; t < NT; ++t) {
;         const int buf = t & 1;
;         if (t + 1 < NT) LOADT(t + 1, buf ^ 1);
;         const int kb = kbase0 + 64 * t;
;         const bool act = (kb <= qlo + 31) && (MLA || kb + 63 >= qlo - (W - 1));
;         if (act) {
;             f32x16 p0 = f32x16{}, p1 = f32x16{};
;             if constexpr (MLA) {
; #pragma unroll
;                 for (int r = 0; r < 16; ++r) { p0[r] = -m_reg; p1[r] = -m_reg; } }
;             if constexpr (MLA) { qk_mla(p0, p1, (int)(uintptr_t)K_lds + buf * KBYTES, r32, hi, qr); }
;             else { qk64(p0, p1, K_lds + buf * KBYTES, r32, hi, qr); }
.Lm16_tile:
	s_and_b32 s58, s41, 1
	s_mul_i32 s70, s58, 0x6000
	s_add_u32 s70, s70, 0x8000
	s_lshl_b32 s71, s58, 14
	s_add_u32 s36, s41, 1
	s_cmp_lt_u32 s36, s40
	s_cbranch_scc0 .Lm16_noload
	s_xor_b32 s37, s58, 1
	s_mul_i32 s59, s37, 0x6000
	s_add_u32 s59, s59, 0x8000
	s_lshl_b32 s37, s37, 14
	s_add_i32 s36, s5, s59
	s_mov_b32 m0, s36
	s_nop 0
	global_load_lds_dwordx4 v232, s[46:47]
	s_add_i32 m0, s36, 0x2000
	s_nop 0
	global_load_lds_dwordx4 v233, s[46:47]
	s_add_i32 m0, s36, 0x4000
	s_nop 0
	global_load_lds_dwordx4 v234, s[50:51]
	s_add_i32 s36, s5, s37
	s_mov_b32 m0, s36
	s_nop 0
	global_load_lds_dwordx4 v235, s[48:49]
	s_add_i32 m0, s36, 0x2000
	s_nop 0
	global_load_lds_dwordx4 v236, s[48:49]
	s_add_u32 s46, s46, 0x40000
	s_addc_u32 s47, s47, 0
	s_add_u32 s48, s48, 0x40000
	s_addc_u32 s49, s49, 0
	s_add_u32 s50, s50, 0x2000
	s_addc_u32 s51, s51, 0
.Lm16_noload:
	s_add_u32 s36, s43, 31
	s_cmp_gt_u32 s42, s36
	s_cbranch_scc1 .Lm16_tile_end
	v_add_u32_e32 v228, s70, v224
	v_add_u32_e32 v230, s71, v226
	v_add_u32_e32 v229, s70, v225
	v_add_u32_e32 v231, s71, v227
	ds_read_b128 v[180:183], v228 offset:0
	ds_read_b128 v[184:187], v228 offset:2048
	ds_read_b128 v[188:191], v228 offset:4096
	ds_read_b128 v[192:195], v228 offset:6144
	s_waitcnt lgkmcnt(3)
	v_mfma_f32_16x16x32_bf16 v[114:117], v[180:183], v[66:69], v[208:211]
	v_mfma_f32_16x16x32_bf16 v[118:121], v[180:183], v[90:93], v[212:215]
	ds_read_b128 v[180:183], v229 offset:0
	s_waitcnt lgkmcnt(3)
	v_mfma_f32_16x16x32_bf16 v[122:125], v[184:187], v[66:69], v[208:211]
	v_mfma_f32_16x16x32_bf16 v[126:129], v[184:187], v[90:93], v[212:215]
	ds_read_b128 v[184:187], v229 offset:2048
	s_waitcnt lgkmcnt(3)
	v_mfma_f32_16x16x32_bf16 v[130:133], v[188:191], v[66:69], v[208:211]
	v_mfma_f32_16x16x32_bf16 v[134:137], v[188:191], v[90:93], v[212:215]
	ds_read_b128 v[188:191], v229 offset:4096
	s_waitcnt lgkmcnt(3)
	v_mfma_f32_16x16x32_bf16 v[138:141], v[192:195], v[66:69], v[208:211]
	v_mfma_f32_16x16x32_bf16 v[142:145], v[192:195], v[90:93], v[212:215]
	ds_read_b128 v[192:195], v229 offset:6144
	s_waitcnt lgkmcnt(3)
	v_mfma_f32_16x16x32_bf16 v[114:117], v[180:183], v[70:73], v[114:117]
	v_mfma_f32_16x16x32_bf16 v[118:121], v[180:183], v[94:97], v[118:121]
	ds_read_b128 v[180:183], v228 offset:8192
	s_waitcnt lgkmcnt(3)
	v_mfma_f32_16x16x32_bf16 v[122:125], v[184:187], v[70:73], v[122:125]
	v_mfma_f32_16x16x32_bf16 v[126:129], v[184:187], v[94:97], v[126:129]
	ds_read_b128 v[184:187], v228 offset:10240
	s_waitcnt lgkmcnt(3)
	v_mfma_f32_16x16x32_bf16 v[130:133], v[188:191], v[70:73], v[130:133]
	v_mfma_f32_16x16x32_bf16 v[134:137], v[188:191], v[94:97], v[134:137]
	ds_read_b128 v[188:191], v228 offset:12288
	s_waitcnt lgkmcnt(3)
	v_mfma_f32_16x16x32_bf16 v[138:141], v[192:195], v[70:73], v[138:141]
	v_mfma_f32_16x16x32_bf16 v[142:145], v[192:195], v[94:97], v[142:145]
	ds_read_b128 v[192:195], v228 offset:14336
	s_waitcnt lgkmcnt(3)
	v_mfma_f32_16x16x32_bf16 v[114:117], v[180:183], v[74:77], v[114:117]
	v_mfma_f32_16x16x32_bf16 v[118:121], v[180:183], v[98:101], v[118:121]
	ds_read_b128 v[180:183], v229 offset:8192
	s_waitcnt lgkmcnt(3)
	v_mfma_f32_16x16x32_bf16 v[122:125], v[184:187], v[74:77], v[122:125]
	v_mfma_f32_16x16x32_bf16 v[126:129], v[184:187], v[98:101], v[126:129]
	ds_read_b128 v[184:187], v229 offset:10240
	s_waitcnt lgkmcnt(3)
	v_mfma_f32_16x16x32_bf16 v[130:133], v[188:191], v[74:77], v[130:133]
	v_mfma_f32_16x16x32_bf16 v[134:137], v[188:191], v[98:101], v[134:137]
	ds_read_b128 v[188:191], v229 offset:12288
	s_waitcnt lgkmcnt(3)
	v_mfma_f32_16x16x32_bf16 v[138:141], v[192:195], v[74:77], v[138:141]
	v_mfma_f32_16x16x32_bf16 v[142:145], v[192:195], v[98:101], v[142:145]
	ds_read_b128 v[192:195], v229 offset:14336
	s_waitcnt lgkmcnt(3)
	v_mfma_f32_16x16x32_bf16 v[114:117], v[180:183], v[78:81], v[114:117]
	v_mfma_f32_16x16x32_bf16 v[118:121], v[180:183], v[102:105], v[118:121]
	ds_read_b128 v[180:183], v228 offset:16384
	s_waitcnt lgkmcnt(3)
	v_mfma_f32_16x16x32_bf16 v[122:125], v[184:187], v[78:81], v[122:125]
	v_mfma_f32_16x16x32_bf16 v[126:129], v[184:187], v[102:105], v[126:129]
	ds_read_b128 v[184:187], v228 offset:18432
	s_waitcnt lgkmcnt(3)
	v_mfma_f32_16x16x32_bf16 v[130:133], v[188:191], v[78:81], v[130:133]
	v_mfma_f32_16x16x32_bf16 v[134:137], v[188:191], v[102:105], v[134:137]
	ds_read_b128 v[188:191], v228 offset:20480
	s_waitcnt lgkmcnt(3)
	v_mfma_f32_16x16x32_bf16 v[138:141], v[192:195], v[78:81], v[138:141]
	v_mfma_f32_16x16x32_bf16 v[142:145], v[192:195], v[102:105], v[142:145]
	ds_read_b128 v[192:195], v228 offset:22528
	s_waitcnt lgkmcnt(3)
	v_mfma_f32_16x16x32_bf16 v[114:117], v[180:183], v[82:85], v[114:117]
	v_mfma_f32_16x16x32_bf16 v[118:121], v[180:183], v[106:109], v[118:121]
	ds_read_b128 v[180:183], v229 offset:16384
	s_waitcnt lgkmcnt(3)
	v_mfma_f32_16x16x32_bf16 v[122:125], v[184:187], v[82:85], v[122:125]
	v_mfma_f32_16x16x32_bf16 v[126:129], v[184:187], v[106:109], v[126:129]
	ds_read_b128 v[184:187], v229 offset:18432
	s_waitcnt lgkmcnt(3)
	v_mfma_f32_16x16x32_bf16 v[130:133], v[188:191], v[82:85], v[130:133]
	v_mfma_f32_16x16x32_bf16 v[134:137], v[188:191], v[106:109], v[134:137]
	ds_read_b128 v[188:191], v229 offset:20480
	s_waitcnt lgkmcnt(3)
	v_mfma_f32_16x16x32_bf16 v[138:141], v[192:195], v[82:85], v[138:141]
	v_mfma_f32_16x16x32_bf16 v[142:145], v[192:195], v[106:109], v[142:145]
	ds_read_b128 v[192:195], v229 offset:22528
	s_waitcnt lgkmcnt(3)
	v_mfma_f32_16x16x32_bf16 v[114:117], v[180:183], v[86:89], v[114:117]
	v_mfma_f32_16x16x32_bf16 v[118:121], v[180:183], v[110:113], v[118:121]
	s_waitcnt lgkmcnt(2)
	v_mfma_f32_16x16x32_bf16 v[122:125], v[184:187], v[86:89], v[122:125]
	v_mfma_f32_16x16x32_bf16 v[126:129], v[184:187], v[110:113], v[126:129]
	s_waitcnt lgkmcnt(1)
	v_mfma_f32_16x16x32_bf16 v[130:133], v[188:191], v[86:89], v[130:133]
	v_mfma_f32_16x16x32_bf16 v[134:137], v[188:191], v[110:113], v[134:137]
	s_waitcnt lgkmcnt(0)
	v_mfma_f32_16x16x32_bf16 v[138:141], v[192:195], v[86:89], v[138:141]
	v_mfma_f32_16x16x32_bf16 v[142:145], v[192:195], v[110:113], v[142:145]
	s_nop 7
	s_add_u32 s36, s42, 63
	s_cmp_gt_u32 s36, s43
	s_cbranch_scc0 .Lm16_nomask
; __device__ __forceinline__ void mask_tile(f32x16& p0, f32x16& p1, int dq, unsigned W) {
;     const float NEG = -__builtin_inff();
; #pragma unroll
;     for (int r = 0; r < 16; ++r) { const int c = (r & 3) + 8 * (r >> 2);
;         if ((unsigned)(dq - c) >= W) p0[r] = NEG;
;         if ((unsigned)(dq - c - 32) >= W) p1[r] = NEG; }
; }
; __device__ __forceinline__ void partialSM_pre(f32x16& p0, f32x16& p1, float& m_reg, float& alpha) {
;     constexpr float THR2 = THR * 1.4426950408889634f;
;     float pmax = p0[0];
; #pragma unroll
;     for (int r = 1; r < 16; ++r) pmax = fmaxf(pmax, p0[r]);
; #pragma unroll
;     for (int r = 0; r < 16; ++r) pmax = fmaxf(pmax, p1[r]);
;     { auto rr = __builtin_amdgcn_permlane32_swap(__float_as_uint(pmax), __float_as_uint(pmax), false, false);
;       pmax = fmaxf(__uint_as_float(rr[0]), __uint_as_float(rr[1])); }
;     if (__builtin_expect(__all(pmax <= THR2), 1)) { alpha = 1.f; }
;     else { const float d = fmaxf(pmax, 0.f); m_reg += d; alpha = __builtin_amdgcn_exp2f(-d);
; #pragma unroll
;         for (int r = 0; r < 16; ++r) { p0[r] -= d; p1[r] -= d; } }
	s_sub_u32 s36, s43, s42
	v_add_u32_e32 v244, s36, v243
	v_cmp_gt_i32_e32 vcc, 0, v244
	s_nop 1
	v_cndmask_b32_e32 v114, v114, v245, vcc
	v_cmp_gt_i32_e32 vcc, 1, v244
	s_nop 1
	v_cndmask_b32_e32 v115, v115, v245, vcc
	v_cmp_gt_i32_e32 vcc, 2, v244
	s_nop 1
	v_cndmask_b32_e32 v116, v116, v245, vcc
	v_cmp_gt_i32_e32 vcc, 3, v244
	s_nop 1
	v_cndmask_b32_e32 v117, v117, v245, vcc
	v_cmp_gt_i32_e32 vcc, -16, v244
	s_nop 1
	v_cndmask_b32_e32 v118, v118, v245, vcc
	v_cmp_gt_i32_e32 vcc, -15, v244
	s_nop 1
	v_cndmask_b32_e32 v119, v119, v245, vcc
	v_cmp_gt_i32_e32 vcc, -14, v244
	s_nop 1
	v_cndmask_b32_e32 v120, v120, v245, vcc
	v_cmp_gt_i32_e32 vcc, -13, v244
	s_nop 1
	v_cndmask_b32_e32 v121, v121, v245, vcc
	v_cmp_gt_i32_e32 vcc, 16, v244
	s_nop 1
	v_cndmask_b32_e32 v122, v122, v245, vcc
	v_cmp_gt_i32_e32 vcc, 17, v244
	s_nop 1
	v_cndmask_b32_e32 v123, v123, v245, vcc
	v_cmp_gt_i32_e32 vcc, 18, v244
	s_nop 1
	v_cndmask_b32_e32 v124, v124, v245, vcc
	v_cmp_gt_i32_e32 vcc, 19, v244
	s_nop 1
	v_cndmask_b32_e32 v125, v125, v245, vcc
	v_cmp_gt_i32_e32 vcc, 0, v244
	s_nop 1
	v_cndmask_b32_e32 v126, v126, v245, vcc
	v_cmp_gt_i32_e32 vcc, 1, v244
	s_nop 1
	v_cndmask_b32_e32 v127, v127, v245, vcc
	v_cmp_gt_i32_e32 vcc, 2, v244
	s_nop 1
	v_cndmask_b32_e32 v128, v128, v245, vcc
	v_cmp_gt_i32_e32 vcc, 3, v244
	s_nop 1
	v_cndmask_b32_e32 v129, v129, v245, vcc
	v_cmp_gt_i32_e32 vcc, 32, v244
	s_nop 1
	v_cndmask_b32_e32 v130, v130, v245, vcc
	v_cmp_gt_i32_e32 vcc, 33, v244
	s_nop 1
	v_cndmask_b32_e32 v131, v131, v245, vcc
	v_cmp_gt_i32_e32 vcc, 34, v244
	s_nop 1
	v_cndmask_b32_e32 v132, v132, v245, vcc
	v_cmp_gt_i32_e32 vcc, 35, v244
	s_nop 1
	v_cndmask_b32_e32 v133, v133, v245, vcc
	v_cmp_gt_i32_e32 vcc, 16, v244
	s_nop 1
	v_cndmask_b32_e32 v134, v134, v245, vcc
	v_cmp_gt_i32_e32 vcc, 17, v244
	s_nop 1
	v_cndmask_b32_e32 v135, v135, v245, vcc
	v_cmp_gt_i32_e32 vcc, 18, v244
	s_nop 1
	v_cndmask_b32_e32 v136, v136, v245, vcc
	v_cmp_gt_i32_e32 vcc, 19, v244
	s_nop 1
	v_cndmask_b32_e32 v137, v137, v245, vcc
	v_cmp_gt_i32_e32 vcc, 48, v244
	s_nop 1
	v_cndmask_b32_e32 v138, v138, v245, vcc
	v_cmp_gt_i32_e32 vcc, 49, v244
	s_nop 1
	v_cndmask_b32_e32 v139, v139, v245, vcc
	v_cmp_gt_i32_e32 vcc, 50, v244
	s_nop 1
	v_cndmask_b32_e32 v140, v140, v245, vcc
	v_cmp_gt_i32_e32 vcc, 51, v244
	s_nop 1
	v_cndmask_b32_e32 v141, v141, v245, vcc
	v_cmp_gt_i32_e32 vcc, 32, v244
	s_nop 1
	v_cndmask_b32_e32 v142, v142, v245, vcc
	v_cmp_gt_i32_e32 vcc, 33, v244
	s_nop 1
	v_cndmask_b32_e32 v143, v143, v245, vcc
	v_cmp_gt_i32_e32 vcc, 34, v244
	s_nop 1
	v_cndmask_b32_e32 v144, v144, v245, vcc
	v_cmp_gt_i32_e32 vcc, 35, v244
	s_nop 1
	v_cndmask_b32_e32 v145, v145, v245, vcc
.Lm16_nomask:
	v_max3_f32 v220, v114, v115, v116
	v_max3_f32 v220, v220, v117, v118
	v_max3_f32 v220, v220, v119, v120
	v_max3_f32 v220, v220, v121, v122
	v_max3_f32 v220, v220, v123, v124
	v_max3_f32 v220, v220, v125, v126
	v_max3_f32 v220, v220, v127, v128
	v_max3_f32 v220, v220, v129, v130
	v_max3_f32 v220, v220, v131, v132
	v_max3_f32 v220, v220, v133, v134
	v_max3_f32 v220, v220, v135, v136
	v_max3_f32 v220, v220, v137, v138
	v_max3_f32 v220, v220, v139, v140
	v_max3_f32 v220, v220, v141, v142
	v_max3_f32 v220, v220, v143, v144
	v_max_f32_e32 v220, v220, v145
	v_cmp_ge_f32_e32 vcc, s72, v220
	s_cmp_eq_u64 vcc, exec
	s_cbranch_scc1 .Lm16_exp
	v_max3_f32 v220, v114, v115, v116
	v_max3_f32 v220, v220, v117, v122
	v_max3_f32 v220, v220, v123, v124
	v_max3_f32 v220, v220, v125, v130
	v_max3_f32 v220, v220, v131, v132
	v_max3_f32 v220, v220, v133, v138
	v_max3_f32 v220, v220, v139, v140
	v_max_f32_e32 v220, v220, v141
	ds_bpermute_b32 v221, v246, v220
	s_waitcnt lgkmcnt(0)
	v_max_f32_e32 v220, v220, v221
	ds_bpermute_b32 v221, v247, v220
	s_waitcnt lgkmcnt(0)
	v_max_f32_e32 v220, v220, v221
	v_max_f32_e32 v221, 0, v220
	v_add_f32_e32 v218, v218, v221
	v_exp_f32_e64 v222, -v221
	v_sub_f32_e32 v114, v114, v221
	v_sub_f32_e32 v115, v115, v221
	v_sub_f32_e32 v116, v116, v221
	v_sub_f32_e32 v117, v117, v221
	v_sub_f32_e32 v122, v122, v221
	v_sub_f32_e32 v123, v123, v221
	v_sub_f32_e32 v124, v124, v221
	v_sub_f32_e32 v125, v125, v221
	v_sub_f32_e32 v130, v130, v221
	v_sub_f32_e32 v131, v131, v221
	v_sub_f32_e32 v132, v132, v221
	v_sub_f32_e32 v133, v133, v221
	v_sub_f32_e32 v138, v138, v221
	v_sub_f32_e32 v139, v139, v221
	v_sub_f32_e32 v140, v140, v221
	v_sub_f32_e32 v141, v141, v221
	v_mul_f32_e32 v216, v216, v222
	v_mul_f32_e32 v2, v2, v222
	v_mul_f32_e32 v3, v3, v222
	v_mul_f32_e32 v4, v4, v222
	v_mul_f32_e32 v5, v5, v222
	v_mul_f32_e32 v10, v10, v222
	v_mul_f32_e32 v11, v11, v222
	v_mul_f32_e32 v12, v12, v222
	v_mul_f32_e32 v13, v13, v222
	v_mul_f32_e32 v18, v18, v222
	v_mul_f32_e32 v19, v19, v222
	v_mul_f32_e32 v20, v20, v222
	v_mul_f32_e32 v21, v21, v222
	v_mul_f32_e32 v26, v26, v222
	v_mul_f32_e32 v27, v27, v222
	v_mul_f32_e32 v28, v28, v222
	v_mul_f32_e32 v29, v29, v222
	v_mul_f32_e32 v34, v34, v222
	v_mul_f32_e32 v35, v35, v222
	v_mul_f32_e32 v36, v36, v222
	v_mul_f32_e32 v37, v37, v222
	v_mul_f32_e32 v42, v42, v222
	v_mul_f32_e32 v43, v43, v222
	v_mul_f32_e32 v44, v44, v222
	v_mul_f32_e32 v45, v45, v222
	v_mul_f32_e32 v50, v50, v222
	v_mul_f32_e32 v51, v51, v222
	v_mul_f32_e32 v52, v52, v222
	v_mul_f32_e32 v53, v53, v222
	v_mul_f32_e32 v58, v58, v222
	v_mul_f32_e32 v59, v59, v222
	v_mul_f32_e32 v60, v60, v222
	v_mul_f32_e32 v61, v61, v222
	v_xor_b32_e32 v208, 0x80000000, v218
	v_xor_b32_e32 v209, 0x80000000, v218
	v_xor_b32_e32 v210, 0x80000000, v218
	v_xor_b32_e32 v211, 0x80000000, v218
	v_max3_f32 v220, v118, v119, v120
	v_max3_f32 v220, v220, v121, v126
	v_max3_f32 v220, v220, v127, v128
	v_max3_f32 v220, v220, v129, v134
	v_max3_f32 v220, v220, v135, v136
	v_max3_f32 v220, v220, v137, v142
	v_max3_f32 v220, v220, v143, v144
	v_max_f32_e32 v220, v220, v145
	ds_bpermute_b32 v221, v246, v220
	s_waitcnt lgkmcnt(0)
; #define PV_RD(S, d0) do { constexpr int b_ = (d0) * 512; TRRD(S##l0, b_); TRRD(S##h0, b_ + KS_ / 2); TRRD(S##l1, b_ + KS_); TRRD(S##h1, b_ + KS_ + KS_ / 2); TRRD(S##l2, b_ + 2 * KS_); TRRD(S##h2, b_ + 2 * KS_ + KS_ / 2); TRRD(S##l3, b_ + 3 * KS_); TRRD(S##h3, b_ + 3 * KS_ + KS_ / 2); } while (0)
; #define WL(n) do { asm volatile("s_waitcnt lgkmcnt(" #n ")" ::: "memory"); SBAR(); } while (0)
; __device__ __forceinline__ void partialSM_pre(f32x16& p0, f32x16& p1, float& m_reg, float& alpha) {
;     ...
; #pragma unroll
;     for (int r = 0; r < 16; ++r) p0[r] = __builtin_amdgcn_exp2f(p0[r]);
; }
; __device__ __forceinline__ void finishSM(f32x16& p0, f32x16& p1, float alpha, float& l_reg, bf16x8& pa0, bf16x8& pa1, bf16x8& pa2, bf16x8& pa3) {
; #pragma unroll
;     for (int r = 0; r < 16; ++r) p1[r] = __builtin_amdgcn_exp2f(p1[r]);
;     float ps = 0;
; #pragma unroll
;     for (int r = 0; r < 16; ++r) ps += p0[r];
; #pragma unroll
;     for (int r = 0; r < 16; ++r) ps += p1[r];
;     { auto rr = __builtin_amdgcn_permlane32_swap(__float_as_uint(ps), __float_as_uint(ps), false, false);
;       ps = __uint_as_float(rr[0]) + __uint_as_float(rr[1]); }
;     l_reg = l_reg * alpha + ps;
; template <int NCB> __device__ __forceinline__ void pv_tile(f32x16* o, int vb, bf16x8 pa0, bf16x8 pa1, bf16x8 pa2, bf16x8 pa3) {
;     ...
;     constexpr int KS_ = NCB * 1024;
;     ...
;     s16x4 Al0, Al1, Al2, Al3, Ah0, Ah1, Ah2, Ah3, Bl0, Bl1, Bl2, Bl3, Bh0, Bh1, Bh2, Bh3;
;     PV_RD(A, 0); PV_RD(B, 1); WL(8); PV_MM(A, 0);
	v_max_f32_e32 v220, v220, v221
	ds_bpermute_b32 v221, v247, v220
	s_waitcnt lgkmcnt(0)
	v_max_f32_e32 v220, v220, v221
	v_max_f32_e32 v221, 0, v220
	v_add_f32_e32 v219, v219, v221
	v_exp_f32_e64 v222, -v221
	v_sub_f32_e32 v118, v118, v221
	v_sub_f32_e32 v119, v119, v221
	v_sub_f32_e32 v120, v120, v221
	v_sub_f32_e32 v121, v121, v221
	v_sub_f32_e32 v126, v126, v221
	v_sub_f32_e32 v127, v127, v221
	v_sub_f32_e32 v128, v128, v221
	v_sub_f32_e32 v129, v129, v221
	v_sub_f32_e32 v134, v134, v221
	v_sub_f32_e32 v135, v135, v221
	v_sub_f32_e32 v136, v136, v221
	v_sub_f32_e32 v137, v137, v221
	v_sub_f32_e32 v142, v142, v221
	v_sub_f32_e32 v143, v143, v221
	v_sub_f32_e32 v144, v144, v221
	v_sub_f32_e32 v145, v145, v221
	v_mul_f32_e32 v217, v217, v222
	v_mul_f32_e32 v6, v6, v222
	v_mul_f32_e32 v7, v7, v222
	v_mul_f32_e32 v8, v8, v222
	v_mul_f32_e32 v9, v9, v222
	v_mul_f32_e32 v14, v14, v222
	v_mul_f32_e32 v15, v15, v222
	v_mul_f32_e32 v16, v16, v222
	v_mul_f32_e32 v17, v17, v222
	v_mul_f32_e32 v22, v22, v222
	v_mul_f32_e32 v23, v23, v222
	v_mul_f32_e32 v24, v24, v222
	v_mul_f32_e32 v25, v25, v222
	v_mul_f32_e32 v30, v30, v222
	v_mul_f32_e32 v31, v31, v222
	v_mul_f32_e32 v32, v32, v222
	v_mul_f32_e32 v33, v33, v222
	v_mul_f32_e32 v38, v38, v222
	v_mul_f32_e32 v39, v39, v222
	v_mul_f32_e32 v40, v40, v222
	v_mul_f32_e32 v41, v41, v222
	v_mul_f32_e32 v46, v46, v222
	v_mul_f32_e32 v47, v47, v222
	v_mul_f32_e32 v48, v48, v222
	v_mul_f32_e32 v49, v49, v222
	v_mul_f32_e32 v54, v54, v222
	v_mul_f32_e32 v55, v55, v222
	v_mul_f32_e32 v56, v56, v222
	v_mul_f32_e32 v57, v57, v222
	v_mul_f32_e32 v62, v62, v222
	v_mul_f32_e32 v63, v63, v222
	v_mul_f32_e32 v64, v64, v222
	v_mul_f32_e32 v65, v65, v222
	v_xor_b32_e32 v212, 0x80000000, v219
	v_xor_b32_e32 v213, 0x80000000, v219
	v_xor_b32_e32 v214, 0x80000000, v219
	v_xor_b32_e32 v215, 0x80000000, v219
.Lm16_exp:
	v_exp_f32_e32 v114, v114
	v_exp_f32_e32 v115, v115
	v_exp_f32_e32 v116, v116
	v_exp_f32_e32 v117, v117
	v_exp_f32_e32 v118, v118
	v_exp_f32_e32 v119, v119
	v_exp_f32_e32 v120, v120
	v_exp_f32_e32 v121, v121
	v_exp_f32_e32 v122, v122
	v_exp_f32_e32 v123, v123
	v_exp_f32_e32 v124, v124
	v_exp_f32_e32 v125, v125
	v_exp_f32_e32 v126, v126
	v_exp_f32_e32 v127, v127
	v_exp_f32_e32 v128, v128
	v_exp_f32_e32 v129, v129
	v_exp_f32_e32 v130, v130
	v_exp_f32_e32 v131, v131
	v_exp_f32_e32 v132, v132
	v_exp_f32_e32 v133, v133
	v_exp_f32_e32 v134, v134
	v_exp_f32_e32 v135, v135
	v_exp_f32_e32 v136, v136
	v_exp_f32_e32 v137, v137
	v_exp_f32_e32 v138, v138
	v_exp_f32_e32 v139, v139
	v_exp_f32_e32 v140, v140
	v_exp_f32_e32 v141, v141
	v_exp_f32_e32 v142, v142
	v_exp_f32_e32 v143, v143
	v_exp_f32_e32 v144, v144
	v_exp_f32_e32 v145, v145
	v_add_f32_e32 v216, v216, v114
	v_add_f32_e32 v217, v217, v118
	v_add_f32_e32 v216, v216, v115
	v_add_f32_e32 v217, v217, v119
	v_add_f32_e32 v216, v216, v116
	v_add_f32_e32 v217, v217, v120
	v_add_f32_e32 v216, v216, v117
	v_add_f32_e32 v217, v217, v121
	v_add_f32_e32 v216, v216, v122
	v_add_f32_e32 v217, v217, v126
	v_add_f32_e32 v216, v216, v123
	v_add_f32_e32 v217, v217, v127
	v_add_f32_e32 v216, v216, v124
	v_add_f32_e32 v217, v217, v128
	v_add_f32_e32 v216, v216, v125
	v_add_f32_e32 v217, v217, v129
	v_add_f32_e32 v216, v216, v130
	v_add_f32_e32 v217, v217, v134
	v_add_f32_e32 v216, v216, v131
	v_add_f32_e32 v217, v217, v135
	v_add_f32_e32 v216, v216, v132
	v_add_f32_e32 v217, v217, v136
	v_add_f32_e32 v216, v216, v133
	v_add_f32_e32 v217, v217, v137
	v_add_f32_e32 v216, v216, v138
	v_add_f32_e32 v217, v217, v142
	v_add_f32_e32 v216, v216, v139
	v_add_f32_e32 v217, v217, v143
	v_add_f32_e32 v216, v216, v140
	v_add_f32_e32 v217, v217, v144
	v_add_f32_e32 v216, v216, v141
	v_add_f32_e32 v217, v217, v145
	v_cvt_pk_bf16_f32 v164, v114, v115
	v_cvt_pk_bf16_f32 v165, v116, v117
	v_cvt_pk_bf16_f32 v166, v122, v123
	v_cvt_pk_bf16_f32 v167, v124, v125
	v_cvt_pk_bf16_f32 v168, v130, v131
	v_cvt_pk_bf16_f32 v169, v132, v133
	v_cvt_pk_bf16_f32 v170, v138, v139
	v_cvt_pk_bf16_f32 v171, v140, v141
	v_cvt_pk_bf16_f32 v172, v118, v119
	v_cvt_pk_bf16_f32 v173, v120, v121
	v_cvt_pk_bf16_f32 v174, v126, v127
	v_cvt_pk_bf16_f32 v175, v128, v129
	v_cvt_pk_bf16_f32 v176, v134, v135
	v_cvt_pk_bf16_f32 v177, v136, v137
	v_cvt_pk_bf16_f32 v178, v142, v143
	v_cvt_pk_bf16_f32 v179, v144, v145
	ds_read_b64_tr_b16 v[180:181], v230 offset:0
	ds_read_b64_tr_b16 v[182:183], v230 offset:4096
	ds_read_b64_tr_b16 v[184:185], v230 offset:8192
	ds_read_b64_tr_b16 v[186:187], v230 offset:12288
	ds_read_b64_tr_b16 v[188:189], v231 offset:0
	ds_read_b64_tr_b16 v[190:191], v231 offset:4096
	ds_read_b64_tr_b16 v[192:193], v231 offset:8192
	ds_read_b64_tr_b16 v[194:195], v231 offset:12288
	s_waitcnt lgkmcnt(6)
	v_mfma_f32_16x16x32_bf16 v[2:5], v[180:183], v[164:167], v[2:5]
	v_mfma_f32_16x16x32_bf16 v[6:9], v[180:183], v[172:175], v[6:9]
	ds_read_b64_tr_b16 v[180:181], v230 offset:512
	ds_read_b64_tr_b16 v[182:183], v230 offset:4608
	s_waitcnt lgkmcnt(6)
	v_mfma_f32_16x16x32_bf16 v[2:5], v[184:187], v[168:171], v[2:5]
	v_mfma_f32_16x16x32_bf16 v[6:9], v[184:187], v[176:179], v[6:9]
	ds_read_b64_tr_b16 v[184:185], v230 offset:8704
	ds_read_b64_tr_b16 v[186:187], v230 offset:12800
	s_waitcnt lgkmcnt(6)
	v_mfma_f32_16x16x32_bf16 v[10:13], v[188:191], v[164:167], v[10:13]
	v_mfma_f32_16x16x32_bf16 v[14:17], v[188:191], v[172:175], v[14:17]
	ds_read_b64_tr_b16 v[188:189], v231 offset:512
	ds_read_b64_tr_b16 v[190:191], v231 offset:4608
	s_waitcnt lgkmcnt(6)
	v_mfma_f32_16x16x32_bf16 v[10:13], v[192:195], v[168:171], v[10:13]
	v_mfma_f32_16x16x32_bf16 v[14:17], v[192:195], v[176:179], v[14:17]
	ds_read_b64_tr_b16 v[192:193], v231 offset:8704
	ds_read_b64_tr_b16 v[194:195], v231 offset:12800
	s_waitcnt lgkmcnt(6)
; #define PV_RD(S, d0) do { constexpr int b_ = (d0) * 512; TRRD(S##l0, b_); TRRD(S##h0, b_ + KS_ / 2); TRRD(S##l1, b_ + KS_); TRRD(S##h1, b_ + KS_ + KS_ / 2); TRRD(S##l2, b_ + 2 * KS_); TRRD(S##h2, b_ + 2 * KS_ + KS_ / 2); TRRD(S##l3, b_ + 3 * KS_); TRRD(S##h3, b_ + 3 * KS_ + KS_ / 2); } while (0)
; #define WL(n) do { asm volatile("s_waitcnt lgkmcnt(" #n ")" ::: "memory"); SBAR(); } while (0)
; template <int NCB> __device__ __forceinline__ void pv_tile(f32x16* o, int vb, bf16x8 pa0, bf16x8 pa1, bf16x8 pa2, bf16x8 pa3) {
;     ...
;     constexpr int KS_ = NCB * 1024;
;     ...
;     s16x4 Al0, Al1, Al2, Al3, Ah0, Ah1, Ah2, Ah3, Bl0, Bl1, Bl2, Bl3, Bh0, Bh1, Bh2, Bh3;
;     PV_RD(A, 0); PV_RD(B, 1); WL(8); PV_MM(A, 0);
;     if constexpr (NCB == 4) { PV_RD(A, 2); WL(8); PV_MM(B, 1); PV_RD(B, 3); WL(8); PV_MM(A, 2); WL(0); PV_MM(B, 3); }
;     else { WL(0); PV_MM(B, 1); }
	v_mfma_f32_16x16x32_bf16 v[18:21], v[180:183], v[164:167], v[18:21]
	v_mfma_f32_16x16x32_bf16 v[22:25], v[180:183], v[172:175], v[22:25]
	ds_read_b64_tr_b16 v[180:181], v230 offset:1024
	ds_read_b64_tr_b16 v[182:183], v230 offset:5120
	s_waitcnt lgkmcnt(6)
	v_mfma_f32_16x16x32_bf16 v[18:21], v[184:187], v[168:171], v[18:21]
	v_mfma_f32_16x16x32_bf16 v[22:25], v[184:187], v[176:179], v[22:25]
	ds_read_b64_tr_b16 v[184:185], v230 offset:9216
	ds_read_b64_tr_b16 v[186:187], v230 offset:13312
	s_waitcnt lgkmcnt(6)
	v_mfma_f32_16x16x32_bf16 v[26:29], v[188:191], v[164:167], v[26:29]
	v_mfma_f32_16x16x32_bf16 v[30:33], v[188:191], v[172:175], v[30:33]
	ds_read_b64_tr_b16 v[188:189], v231 offset:1024
	ds_read_b64_tr_b16 v[190:191], v231 offset:5120
	s_waitcnt lgkmcnt(6)
	v_mfma_f32_16x16x32_bf16 v[26:29], v[192:195], v[168:171], v[26:29]
	v_mfma_f32_16x16x32_bf16 v[30:33], v[192:195], v[176:179], v[30:33]
	ds_read_b64_tr_b16 v[192:193], v231 offset:9216
	ds_read_b64_tr_b16 v[194:195], v231 offset:13312
	s_waitcnt lgkmcnt(6)
	v_mfma_f32_16x16x32_bf16 v[34:37], v[180:183], v[164:167], v[34:37]
	v_mfma_f32_16x16x32_bf16 v[38:41], v[180:183], v[172:175], v[38:41]
	ds_read_b64_tr_b16 v[180:181], v230 offset:1536
	ds_read_b64_tr_b16 v[182:183], v230 offset:5632
	s_waitcnt lgkmcnt(6)
	v_mfma_f32_16x16x32_bf16 v[34:37], v[184:187], v[168:171], v[34:37]
	v_mfma_f32_16x16x32_bf16 v[38:41], v[184:187], v[176:179], v[38:41]
	ds_read_b64_tr_b16 v[184:185], v230 offset:9728
	ds_read_b64_tr_b16 v[186:187], v230 offset:13824
	s_waitcnt lgkmcnt(6)
	v_mfma_f32_16x16x32_bf16 v[42:45], v[188:191], v[164:167], v[42:45]
	v_mfma_f32_16x16x32_bf16 v[46:49], v[188:191], v[172:175], v[46:49]
	ds_read_b64_tr_b16 v[188:189], v231 offset:1536
	ds_read_b64_tr_b16 v[190:191], v231 offset:5632
	s_waitcnt lgkmcnt(6)
	v_mfma_f32_16x16x32_bf16 v[42:45], v[192:195], v[168:171], v[42:45]
	v_mfma_f32_16x16x32_bf16 v[46:49], v[192:195], v[176:179], v[46:49]
	ds_read_b64_tr_b16 v[192:193], v231 offset:9728
	ds_read_b64_tr_b16 v[194:195], v231 offset:13824
	s_waitcnt lgkmcnt(6)
	v_mfma_f32_16x16x32_bf16 v[50:53], v[180:183], v[164:167], v[50:53]
	v_mfma_f32_16x16x32_bf16 v[54:57], v[180:183], v[172:175], v[54:57]
	s_waitcnt lgkmcnt(4)
	v_mfma_f32_16x16x32_bf16 v[50:53], v[184:187], v[168:171], v[50:53]
	v_mfma_f32_16x16x32_bf16 v[54:57], v[184:187], v[176:179], v[54:57]
	s_waitcnt lgkmcnt(2)
	v_mfma_f32_16x16x32_bf16 v[58:61], v[188:191], v[164:167], v[58:61]
	v_mfma_f32_16x16x32_bf16 v[62:65], v[188:191], v[172:175], v[62:65]
	s_waitcnt lgkmcnt(0)
	v_mfma_f32_16x16x32_bf16 v[58:61], v[192:195], v[168:171], v[58:61]
	v_mfma_f32_16x16x32_bf16 v[62:65], v[192:195], v[176:179], v[62:65]
; #define LAS __attribute__((address_space(3)))
; __device__ __forceinline__ int crow(int r, int hi) { return (r & 3) + 8 * (r >> 2) + 4 * hi; }
; __device__ __forceinline__ unsigned cvtpk(float lo, float hi) { f32x2_cv v = {lo, hi}; bf16x2_cv b = __builtin_convertvector(v, bf16x2_cv); return __builtin_bit_cast(unsigned, b); }
; template <bool MLA> __device__ __forceinline__ void attn_unit(const AttnP& P, int b, int hh, int qb, LAS char* lds) {
;     ...
;         __syncthreads();
;     }
;     if (hi == 0) li_l[r32] = l_reg; asm volatile("s_waitcnt lgkmcnt(0)" ::: "memory");
;     bf16_t* Ow = (MLA ? P.QN + (rowbase + qlo) * 2048 + hh * 128 : P.QS + (rowbase + qlo) * 2048 + hh * 64);
; #pragma unroll
;     for (int r = 0; r < 16; ++r) { const int orow = crow(r, hi); const float rl = __builtin_amdgcn_rcpf(li_l[orow]);
; #pragma unroll
;         for (int d0 = 0; d0 < NCB; ++d0) { const float v = o[d0][r] * rl; const float vn = __shfl_xor(v, 1);
;             if ((r32 & 1) == 0) *(unsigned*)(Ow + (size_t)orow * 2048 + d0 * 32 + r32) = cvtpk(v, vn); } }
;     __syncthreads();
; __global__ void __launch_bounds__(512) fwd_mega(Args a) {
;     ...
;         for (int it = vcu; it < 1024; it += G) { const int bh = it >> 5, s = it & 31;
;             att::attn_unit<true>(P, bh >> 4, bh & 15, 63 - s, (LAS char*)lds);
;             att::attn_unit<true>(P, bh >> 4, bh & 15, s, (LAS char*)lds); }
.Lm16_tile_end:
	s_waitcnt vmcnt(0) lgkmcnt(0)
	s_barrier
	s_add_u32 s41, s41, 1
	s_add_u32 s42, s42, 64
	s_cmp_lt_u32 s41, s40
	s_cbranch_scc1 .Lm16_tile
	s_nop 7
	ds_bpermute_b32 v221, v246, v216
	s_waitcnt lgkmcnt(0)
	v_add_f32_e32 v216, v216, v221
	ds_bpermute_b32 v221, v247, v216
	s_waitcnt lgkmcnt(0)
	v_add_f32_e32 v216, v216, v221
	v_rcp_f32_e32 v216, v216
	ds_bpermute_b32 v221, v246, v217
	s_waitcnt lgkmcnt(0)
	v_add_f32_e32 v217, v217, v221
	ds_bpermute_b32 v221, v247, v217
	s_waitcnt lgkmcnt(0)
	v_add_f32_e32 v217, v217, v221
	v_rcp_f32_e32 v217, v217
	s_nop 0
	v_mul_f32_e32 v2, v2, v216
	v_mul_f32_e32 v3, v3, v216
	v_mul_f32_e32 v4, v4, v216
	v_mul_f32_e32 v5, v5, v216
	v_cvt_pk_bf16_f32 v2, v2, v3
	v_cvt_pk_bf16_f32 v3, v4, v5
	global_store_dwordx2 v241, v[2:3], s[66:67] offset:0
	v_mul_f32_e32 v6, v6, v217
	v_mul_f32_e32 v7, v7, v217
	v_mul_f32_e32 v8, v8, v217
	v_mul_f32_e32 v9, v9, v217
	v_cvt_pk_bf16_f32 v6, v6, v7
	v_cvt_pk_bf16_f32 v7, v8, v9
	global_store_dwordx2 v242, v[6:7], s[66:67] offset:0
	v_mul_f32_e32 v10, v10, v216
	v_mul_f32_e32 v11, v11, v216
	v_mul_f32_e32 v12, v12, v216
	v_mul_f32_e32 v13, v13, v216
	v_cvt_pk_bf16_f32 v10, v10, v11
	v_cvt_pk_bf16_f32 v11, v12, v13
	global_store_dwordx2 v241, v[10:11], s[66:67] offset:32
	v_mul_f32_e32 v14, v14, v217
	v_mul_f32_e32 v15, v15, v217
	v_mul_f32_e32 v16, v16, v217
	v_mul_f32_e32 v17, v17, v217
	v_cvt_pk_bf16_f32 v14, v14, v15
	v_cvt_pk_bf16_f32 v15, v16, v17
	global_store_dwordx2 v242, v[14:15], s[66:67] offset:32
	v_mul_f32_e32 v18, v18, v216
	v_mul_f32_e32 v19, v19, v216
	v_mul_f32_e32 v20, v20, v216
	v_mul_f32_e32 v21, v21, v216
	v_cvt_pk_bf16_f32 v18, v18, v19
	v_cvt_pk_bf16_f32 v19, v20, v21
	global_store_dwordx2 v241, v[18:19], s[66:67] offset:64
	v_mul_f32_e32 v22, v22, v217
	v_mul_f32_e32 v23, v23, v217
	v_mul_f32_e32 v24, v24, v217
	v_mul_f32_e32 v25, v25, v217
	v_cvt_pk_bf16_f32 v22, v22, v23
	v_cvt_pk_bf16_f32 v23, v24, v25
	global_store_dwordx2 v242, v[22:23], s[66:67] offset:64
	v_mul_f32_e32 v26, v26, v216
	v_mul_f32_e32 v27, v27, v216
	v_mul_f32_e32 v28, v28, v216
	v_mul_f32_e32 v29, v29, v216
	v_cvt_pk_bf16_f32 v26, v26, v27
	v_cvt_pk_bf16_f32 v27, v28, v29
	global_store_dwordx2 v241, v[26:27], s[66:67] offset:96
	v_mul_f32_e32 v30, v30, v217
	v_mul_f32_e32 v31, v31, v217
	v_mul_f32_e32 v32, v32, v217
	v_mul_f32_e32 v33, v33, v217
	v_cvt_pk_bf16_f32 v30, v30, v31
	v_cvt_pk_bf16_f32 v31, v32, v33
	global_store_dwordx2 v242, v[30:31], s[66:67] offset:96
	v_mul_f32_e32 v34, v34, v216
	v_mul_f32_e32 v35, v35, v216
	v_mul_f32_e32 v36, v36, v216
	v_mul_f32_e32 v37, v37, v216
	v_cvt_pk_bf16_f32 v34, v34, v35
	v_cvt_pk_bf16_f32 v35, v36, v37
	global_store_dwordx2 v241, v[34:35], s[66:67] offset:128
	v_mul_f32_e32 v38, v38, v217
	v_mul_f32_e32 v39, v39, v217
	v_mul_f32_e32 v40, v40, v217
	v_mul_f32_e32 v41, v41, v217
	v_cvt_pk_bf16_f32 v38, v38, v39
	v_cvt_pk_bf16_f32 v39, v40, v41
	global_store_dwordx2 v242, v[38:39], s[66:67] offset:128
	v_mul_f32_e32 v42, v42, v216
	v_mul_f32_e32 v43, v43, v216
	v_mul_f32_e32 v44, v44, v216
	v_mul_f32_e32 v45, v45, v216
	v_cvt_pk_bf16_f32 v42, v42, v43
	v_cvt_pk_bf16_f32 v43, v44, v45
	global_store_dwordx2 v241, v[42:43], s[66:67] offset:160
	v_mul_f32_e32 v46, v46, v217
	v_mul_f32_e32 v47, v47, v217
	v_mul_f32_e32 v48, v48, v217
	v_mul_f32_e32 v49, v49, v217
	v_cvt_pk_bf16_f32 v46, v46, v47
	v_cvt_pk_bf16_f32 v47, v48, v49
	global_store_dwordx2 v242, v[46:47], s[66:67] offset:160
	v_mul_f32_e32 v50, v50, v216
	v_mul_f32_e32 v51, v51, v216
	v_mul_f32_e32 v52, v52, v216
	v_mul_f32_e32 v53, v53, v216
	v_cvt_pk_bf16_f32 v50, v50, v51
	v_cvt_pk_bf16_f32 v51, v52, v53
	global_store_dwordx2 v241, v[50:51], s[66:67] offset:192
	v_mul_f32_e32 v54, v54, v217
	v_mul_f32_e32 v55, v55, v217
	v_mul_f32_e32 v56, v56, v217
	v_mul_f32_e32 v57, v57, v217
	v_cvt_pk_bf16_f32 v54, v54, v55
	v_cvt_pk_bf16_f32 v55, v56, v57
	global_store_dwordx2 v242, v[54:55], s[66:67] offset:192
	v_mul_f32_e32 v58, v58, v216
	v_mul_f32_e32 v59, v59, v216
	v_mul_f32_e32 v60, v60, v216
	v_mul_f32_e32 v61, v61, v216
	v_cvt_pk_bf16_f32 v58, v58, v59
	v_cvt_pk_bf16_f32 v59, v60, v61
	global_store_dwordx2 v241, v[58:59], s[66:67] offset:224
	v_mul_f32_e32 v62, v62, v217
	v_mul_f32_e32 v63, v63, v217
	v_mul_f32_e32 v64, v64, v217
	v_mul_f32_e32 v65, v65, v217
	v_cvt_pk_bf16_f32 v62, v62, v63
	v_cvt_pk_bf16_f32 v63, v64, v65
	global_store_dwordx2 v242, v[62:63], s[66:67] offset:224
	s_add_u32 s29, s29, 1
	s_cmp_lt_u32 s29, 2
	s_cbranch_scc1 .Lm16_unit
	s_add_u32 s28, s28, s3
	s_cmp_lt_u32 s28, 0x400
	s_cbranch_scc1 .Lm16_item
	s_waitcnt vmcnt(0) lgkmcnt(0)
